# combo, phase-C balance k=0 (every WG exactly one unit)
# baseline (speedup 1.0000x reference)
; __global__ void __launch_bounds__(256, 2) hybrid_megakernel(Params p) {
;     ...
;       int start = 0, mine = 0;
;       for (int g2 = 0; g2 <= gi; ++g2) {
;         const int n = 32 - g2;
;         const int d = (n <= 10) ? 2 : (n <= 22) ? 1 : 0;
;         if (g2 < gi) start += 2 * d; else mine = d;
;       }
;       start += ((vb >> 3) & 1) * mine;
.LBB0_407:
	s_cmp_ge_u32 s2, 0
	s_cselect_b64 s[4:5], -1, 0
	s_cmp_lt_u32 s2, 32
	v_cndmask_b32_e64 v1, 0, 1, s[4:5]
	s_cselect_b64 vcc, -1, 0
	v_cndmask_b32_e32 v1, 2, v1, vcc
	s_cmp_lt_i32 s2, s0
	v_lshlrev_b32_e32 v2, 1, v1
	s_cselect_b64 vcc, -1, 0
	s_add_i32 s2, s2, 1
	v_cndmask_b32_e32 v2, 0, v2, vcc
	v_cndmask_b32_e32 v116, v1, v116, vcc
	s_cmp_eq_u32 s1, s2
	v_add_u32_e32 v0, v2, v0
	s_cbranch_scc0 .LBB0_407
	v_cmp_gt_i32_e32 vcc, 1, v116
	s_cbranch_vccz .LBB0_410
	s_branch .LBB0_345
